# scan consumer: odd-step wait replaces the s_nop filler between DPP adds (6 fewer instructions per chunk); nt row loads kept
# baseline (speedup 1.0000x reference)
.Lscan_chunk:
	s_waitcnt lgkmcnt(5)
	v_pk_mul_f32 v[0:1], v[58:59], v[0:1] op_sel_hi:[0,1]
	v_pk_fma_f32 v[0:1], v[58:59], v[2:3], v[0:1] op_sel:[1,0,0] op_sel_hi:[1,1,1]
	v_pk_fma_f32 v[0:1], v[60:61], v[16:17], v[0:1] op_sel_hi:[0,1,1]
	v_pk_fma_f32 v[0:1], v[60:61], v[18:19], v[0:1] op_sel:[1,0,0] op_sel_hi:[1,1,1]
	ds_write2st64_b32 v72, v81, v1 offset0:28 offset1:30
	v_mov_b32_e32 v72, v67
	v_add_f32_dpp v0, v0, v0 quad_perm:[1,0,3,2] row_mask:0xf bank_mask:0xf bound_ctrl:1
	v_pk_fma_f32 v[12:13], v[58:59], v[4:5], v[12:13]
	ds_read_b128 v[80:83], v74 offset:9216
	v_add_f32_dpp v0, v0, v0 quad_perm:[2,3,0,1] row_mask:0xf bank_mask:0xf bound_ctrl:1
	ds_read_b128 v[96:99], v74 offset:9472
	ds_read_b128 v[84:87], v74 offset:9728
	v_add_f32_dpp v0, v0, v0 row_half_mirror row_mask:0xf bank_mask:0xf bound_ctrl:1
	ds_read_b128 v[92:95], v75 offset:9216
	ds_read_b128 v[88:91], v74 offset:9984
	v_add_f32_dpp v0, v0, v0 row_mirror row_mask:0xf bank_mask:0xf bound_ctrl:1
	v_pk_fma_f32 v[14:15], v[60:61], v[6:7], v[14:15]
	v_pk_fma_f32 v[58:59], v[8:9], v[0:1], v[12:13] op_sel_hi:[1,0,1]
	v_pk_fma_f32 v[60:61], v[10:11], v[0:1], v[14:15] op_sel_hi:[1,0,1]
	v_pk_mul_f32 v[20:21], v[58:59], v[20:21] op_sel_hi:[0,1]
	v_pk_fma_f32 v[20:21], v[58:59], v[22:23], v[20:21] op_sel:[1,0,0] op_sel_hi:[1,1,1]
	v_pk_fma_f32 v[20:21], v[60:61], v[36:37], v[20:21] op_sel_hi:[0,1,1]
	v_pk_fma_f32 v[20:21], v[60:61], v[38:39], v[20:21] op_sel:[1,0,0] op_sel_hi:[1,1,1]
	v_pk_fma_f32 v[32:33], v[58:59], v[24:25], v[32:33]
	v_pk_fma_f32 v[34:35], v[60:61], v[26:27], v[34:35]
	v_add_f32_dpp v20, v20, v20 quad_perm:[1,0,3,2] row_mask:0xf bank_mask:0xf bound_ctrl:1
	ds_read_b128 v[0:3], v74 offset:12288
	ds_read_b128 v[16:19], v74 offset:12544
	v_add_f32_dpp v20, v20, v20 quad_perm:[2,3,0,1] row_mask:0xf bank_mask:0xf bound_ctrl:1
	ds_read_b128 v[4:7], v74 offset:12800
	ds_read_b128 v[12:15], v75 offset:12288
	v_add_f32_dpp v20, v20, v20 row_half_mirror row_mask:0xf bank_mask:0xf bound_ctrl:1
	ds_read_b128 v[8:11], v74 offset:13056
	s_waitcnt lgkmcnt(5)
	v_add_f32_dpp v20, v20, v20 row_mirror row_mask:0xf bank_mask:0xf bound_ctrl:1
	v_pk_fma_f32 v[58:59], v[28:29], v[20:21], v[32:33] op_sel_hi:[1,0,1]
	v_pk_fma_f32 v[60:61], v[30:31], v[20:21], v[34:35] op_sel_hi:[1,0,1]
	v_pk_mul_f32 v[46:47], v[58:59], v[46:47] op_sel_hi:[0,1]
	v_pk_fma_f32 v[46:47], v[58:59], v[48:49], v[46:47] op_sel:[1,0,0] op_sel_hi:[1,1,1]
	v_pk_fma_f32 v[46:47], v[60:61], v[76:77], v[46:47] op_sel_hi:[0,1,1]
	v_pk_fma_f32 v[46:47], v[60:61], v[78:79], v[46:47] op_sel:[1,0,0] op_sel_hi:[1,1,1]
	ds_write2st64_b32 v72, v21, v47 offset0:0 offset1:2
	v_pk_fma_f32 v[68:69], v[58:59], v[50:51], v[68:69]
	v_add_f32_dpp v46, v46, v46 quad_perm:[1,0,3,2] row_mask:0xf bank_mask:0xf bound_ctrl:1
	ds_read_b128 v[20:23], v74 offset:15360
	ds_read_b128 v[36:39], v74 offset:15616
	v_add_f32_dpp v46, v46, v46 quad_perm:[2,3,0,1] row_mask:0xf bank_mask:0xf bound_ctrl:1
	ds_read_b128 v[24:27], v74 offset:15872
	ds_read_b128 v[32:35], v75 offset:15360
	v_add_f32_dpp v46, v46, v46 row_half_mirror row_mask:0xf bank_mask:0xf bound_ctrl:1
	ds_read_b128 v[28:31], v74 offset:16128
	v_pk_fma_f32 v[70:71], v[60:61], v[52:53], v[70:71]
	v_add_f32_dpp v46, v46, v46 row_mirror row_mask:0xf bank_mask:0xf bound_ctrl:1
	v_pk_fma_f32 v[58:59], v[54:55], v[46:47], v[68:69] op_sel_hi:[1,0,1]
	v_pk_fma_f32 v[60:61], v[56:57], v[46:47], v[70:71] op_sel_hi:[1,0,1]
	v_pk_mul_f32 v[80:81], v[58:59], v[80:81] op_sel_hi:[0,1]
	v_pk_fma_f32 v[80:81], v[58:59], v[82:83], v[80:81] op_sel:[1,0,0] op_sel_hi:[1,1,1]
	v_pk_fma_f32 v[80:81], v[60:61], v[96:97], v[80:81] op_sel_hi:[0,1,1]
	v_pk_fma_f32 v[80:81], v[60:61], v[98:99], v[80:81] op_sel:[1,0,0] op_sel_hi:[1,1,1]
	v_pk_fma_f32 v[92:93], v[58:59], v[84:85], v[92:93]
	v_pk_fma_f32 v[94:95], v[60:61], v[86:87], v[94:95]
	v_add_f32_dpp v80, v80, v80 quad_perm:[1,0,3,2] row_mask:0xf bank_mask:0xf bound_ctrl:1
	ds_read_b128 v[46:49], v74 offset:18432
	ds_read_b128 v[76:79], v74 offset:18688
	v_add_f32_dpp v80, v80, v80 quad_perm:[2,3,0,1] row_mask:0xf bank_mask:0xf bound_ctrl:1
	ds_read_b128 v[50:53], v74 offset:18944
	ds_read_b128 v[68:71], v75 offset:18432
	v_add_f32_dpp v80, v80, v80 row_half_mirror row_mask:0xf bank_mask:0xf bound_ctrl:1
	ds_read_b128 v[54:57], v74 offset:19200
	s_waitcnt lgkmcnt(5)
	v_add_f32_dpp v80, v80, v80 row_mirror row_mask:0xf bank_mask:0xf bound_ctrl:1
	v_pk_fma_f32 v[58:59], v[88:89], v[80:81], v[92:93] op_sel_hi:[1,0,1]
	v_pk_fma_f32 v[60:61], v[90:91], v[80:81], v[94:95] op_sel_hi:[1,0,1]
	v_pk_mul_f32 v[0:1], v[58:59], v[0:1] op_sel_hi:[0,1]
	v_pk_fma_f32 v[0:1], v[58:59], v[2:3], v[0:1] op_sel:[1,0,0] op_sel_hi:[1,1,1]
	v_pk_fma_f32 v[0:1], v[60:61], v[16:17], v[0:1] op_sel_hi:[0,1,1]
	v_pk_fma_f32 v[0:1], v[60:61], v[18:19], v[0:1] op_sel:[1,0,0] op_sel_hi:[1,1,1]
	ds_write2st64_b32 v72, v81, v1 offset0:4 offset1:6
	v_pk_fma_f32 v[12:13], v[58:59], v[4:5], v[12:13]
	v_add_f32_dpp v0, v0, v0 quad_perm:[1,0,3,2] row_mask:0xf bank_mask:0xf bound_ctrl:1
	ds_read_b128 v[80:83], v74 offset:21504
	ds_read_b128 v[96:99], v74 offset:21760
	v_add_f32_dpp v0, v0, v0 quad_perm:[2,3,0,1] row_mask:0xf bank_mask:0xf bound_ctrl:1
	ds_read_b128 v[84:87], v74 offset:22016
	ds_read_b128 v[92:95], v75 offset:21504
	v_add_f32_dpp v0, v0, v0 row_half_mirror row_mask:0xf bank_mask:0xf bound_ctrl:1
	ds_read_b128 v[88:91], v74 offset:22272
	v_pk_fma_f32 v[14:15], v[60:61], v[6:7], v[14:15]
	v_add_f32_dpp v0, v0, v0 row_mirror row_mask:0xf bank_mask:0xf bound_ctrl:1
	v_pk_fma_f32 v[58:59], v[8:9], v[0:1], v[12:13] op_sel_hi:[1,0,1]
	v_pk_fma_f32 v[60:61], v[10:11], v[0:1], v[14:15] op_sel_hi:[1,0,1]
	v_pk_mul_f32 v[20:21], v[58:59], v[20:21] op_sel_hi:[0,1]
	v_pk_fma_f32 v[20:21], v[58:59], v[22:23], v[20:21] op_sel:[1,0,0] op_sel_hi:[1,1,1]
	v_pk_fma_f32 v[20:21], v[60:61], v[36:37], v[20:21] op_sel_hi:[0,1,1]
	v_pk_fma_f32 v[20:21], v[60:61], v[38:39], v[20:21] op_sel:[1,0,0] op_sel_hi:[1,1,1]
	v_pk_fma_f32 v[32:33], v[58:59], v[24:25], v[32:33]
	v_pk_fma_f32 v[34:35], v[60:61], v[26:27], v[34:35]
	v_add_f32_dpp v20, v20, v20 quad_perm:[1,0,3,2] row_mask:0xf bank_mask:0xf bound_ctrl:1
	ds_read_b128 v[0:3], v74 offset:24576
	ds_read_b128 v[16:19], v74 offset:24832
	v_add_f32_dpp v20, v20, v20 quad_perm:[2,3,0,1] row_mask:0xf bank_mask:0xf bound_ctrl:1
	ds_read_b128 v[4:7], v74 offset:25088
	ds_read_b128 v[12:15], v75 offset:24576
	v_add_f32_dpp v20, v20, v20 row_half_mirror row_mask:0xf bank_mask:0xf bound_ctrl:1
	ds_read_b128 v[8:11], v74 offset:25344
	s_waitcnt lgkmcnt(5)
	v_add_f32_dpp v20, v20, v20 row_mirror row_mask:0xf bank_mask:0xf bound_ctrl:1
	v_pk_fma_f32 v[58:59], v[28:29], v[20:21], v[32:33] op_sel_hi:[1,0,1]
	v_pk_fma_f32 v[60:61], v[30:31], v[20:21], v[34:35] op_sel_hi:[1,0,1]
	v_pk_mul_f32 v[46:47], v[58:59], v[46:47] op_sel_hi:[0,1]
	v_pk_fma_f32 v[46:47], v[58:59], v[48:49], v[46:47] op_sel:[1,0,0] op_sel_hi:[1,1,1]
	v_pk_fma_f32 v[46:47], v[60:61], v[76:77], v[46:47] op_sel_hi:[0,1,1]
	v_pk_fma_f32 v[46:47], v[60:61], v[78:79], v[46:47] op_sel:[1,0,0] op_sel_hi:[1,1,1]
	ds_write2st64_b32 v72, v21, v47 offset0:8 offset1:10
	v_pk_fma_f32 v[68:69], v[58:59], v[50:51], v[68:69]
	v_add_f32_dpp v46, v46, v46 quad_perm:[1,0,3,2] row_mask:0xf bank_mask:0xf bound_ctrl:1
	ds_read_b128 v[20:23], v74 offset:27648
	ds_read_b128 v[36:39], v74 offset:27904
	v_add_f32_dpp v46, v46, v46 quad_perm:[2,3,0,1] row_mask:0xf bank_mask:0xf bound_ctrl:1
	ds_read_b128 v[24:27], v74 offset:28160
	ds_read_b128 v[32:35], v75 offset:27648
	v_add_f32_dpp v46, v46, v46 row_half_mirror row_mask:0xf bank_mask:0xf bound_ctrl:1
	ds_read_b128 v[28:31], v74 offset:28416
	v_pk_fma_f32 v[70:71], v[60:61], v[52:53], v[70:71]
	v_add_f32_dpp v46, v46, v46 row_mirror row_mask:0xf bank_mask:0xf bound_ctrl:1
	v_pk_fma_f32 v[58:59], v[54:55], v[46:47], v[68:69] op_sel_hi:[1,0,1]
	v_pk_fma_f32 v[60:61], v[56:57], v[46:47], v[70:71] op_sel_hi:[1,0,1]
	v_pk_mul_f32 v[80:81], v[58:59], v[80:81] op_sel_hi:[0,1]
	v_pk_fma_f32 v[80:81], v[58:59], v[82:83], v[80:81] op_sel:[1,0,0] op_sel_hi:[1,1,1]
	v_pk_fma_f32 v[80:81], v[60:61], v[96:97], v[80:81] op_sel_hi:[0,1,1]
	v_pk_fma_f32 v[80:81], v[60:61], v[98:99], v[80:81] op_sel:[1,0,0] op_sel_hi:[1,1,1]
	v_pk_fma_f32 v[92:93], v[58:59], v[84:85], v[92:93]
	v_pk_fma_f32 v[94:95], v[60:61], v[86:87], v[94:95]
	v_add_f32_dpp v80, v80, v80 quad_perm:[1,0,3,2] row_mask:0xf bank_mask:0xf bound_ctrl:1
	ds_read_b128 v[46:49], v74 offset:30720
	ds_read_b128 v[76:79], v74 offset:30976
	v_add_f32_dpp v80, v80, v80 quad_perm:[2,3,0,1] row_mask:0xf bank_mask:0xf bound_ctrl:1
	ds_read_b128 v[50:53], v74 offset:31232
	ds_read_b128 v[68:71], v75 offset:30720
	v_add_f32_dpp v80, v80, v80 row_half_mirror row_mask:0xf bank_mask:0xf bound_ctrl:1
	ds_read_b128 v[54:57], v74 offset:31488
	s_waitcnt lgkmcnt(5)
	v_add_f32_dpp v80, v80, v80 row_mirror row_mask:0xf bank_mask:0xf bound_ctrl:1
	v_pk_fma_f32 v[58:59], v[88:89], v[80:81], v[92:93] op_sel_hi:[1,0,1]
	v_pk_fma_f32 v[60:61], v[90:91], v[80:81], v[94:95] op_sel_hi:[1,0,1]
	v_pk_mul_f32 v[0:1], v[58:59], v[0:1] op_sel_hi:[0,1]
	v_pk_fma_f32 v[0:1], v[58:59], v[2:3], v[0:1] op_sel:[1,0,0] op_sel_hi:[1,1,1]
	v_pk_fma_f32 v[0:1], v[60:61], v[16:17], v[0:1] op_sel_hi:[0,1,1]
	v_pk_fma_f32 v[0:1], v[60:61], v[18:19], v[0:1] op_sel:[1,0,0] op_sel_hi:[1,1,1]
	ds_write2st64_b32 v72, v81, v1 offset0:12 offset1:14
	v_pk_fma_f32 v[12:13], v[58:59], v[4:5], v[12:13]
	v_add_f32_dpp v0, v0, v0 quad_perm:[1,0,3,2] row_mask:0xf bank_mask:0xf bound_ctrl:1
	ds_read_b128 v[80:83], v74 offset:33792
	ds_read_b128 v[96:99], v74 offset:34048
	v_add_f32_dpp v0, v0, v0 quad_perm:[2,3,0,1] row_mask:0xf bank_mask:0xf bound_ctrl:1
	ds_read_b128 v[84:87], v74 offset:34304
	ds_read_b128 v[92:95], v75 offset:33792
	v_add_f32_dpp v0, v0, v0 row_half_mirror row_mask:0xf bank_mask:0xf bound_ctrl:1
	ds_read_b128 v[88:91], v74 offset:34560
	v_pk_fma_f32 v[14:15], v[60:61], v[6:7], v[14:15]
	v_add_f32_dpp v0, v0, v0 row_mirror row_mask:0xf bank_mask:0xf bound_ctrl:1
	v_pk_fma_f32 v[58:59], v[8:9], v[0:1], v[12:13] op_sel_hi:[1,0,1]
	v_pk_fma_f32 v[60:61], v[10:11], v[0:1], v[14:15] op_sel_hi:[1,0,1]
	v_pk_mul_f32 v[20:21], v[58:59], v[20:21] op_sel_hi:[0,1]
	v_pk_fma_f32 v[20:21], v[58:59], v[22:23], v[20:21] op_sel:[1,0,0] op_sel_hi:[1,1,1]
	v_pk_fma_f32 v[20:21], v[60:61], v[36:37], v[20:21] op_sel_hi:[0,1,1]
	v_pk_fma_f32 v[20:21], v[60:61], v[38:39], v[20:21] op_sel:[1,0,0] op_sel_hi:[1,1,1]
	v_pk_fma_f32 v[32:33], v[58:59], v[24:25], v[32:33]
	v_pk_fma_f32 v[34:35], v[60:61], v[26:27], v[34:35]
	v_add_f32_dpp v20, v20, v20 quad_perm:[1,0,3,2] row_mask:0xf bank_mask:0xf bound_ctrl:1
	ds_read_b128 v[0:3], v74 offset:36864
	ds_read_b128 v[16:19], v74 offset:37120
	v_add_f32_dpp v20, v20, v20 quad_perm:[2,3,0,1] row_mask:0xf bank_mask:0xf bound_ctrl:1
	ds_read_b128 v[4:7], v74 offset:37376
	ds_read_b128 v[12:15], v75 offset:36864
	v_add_f32_dpp v20, v20, v20 row_half_mirror row_mask:0xf bank_mask:0xf bound_ctrl:1
	ds_read_b128 v[8:11], v74 offset:37632
	s_waitcnt lgkmcnt(5)
	v_add_f32_dpp v20, v20, v20 row_mirror row_mask:0xf bank_mask:0xf bound_ctrl:1
	v_pk_fma_f32 v[58:59], v[28:29], v[20:21], v[32:33] op_sel_hi:[1,0,1]
	v_pk_fma_f32 v[60:61], v[30:31], v[20:21], v[34:35] op_sel_hi:[1,0,1]
	v_pk_mul_f32 v[46:47], v[58:59], v[46:47] op_sel_hi:[0,1]
	v_pk_fma_f32 v[46:47], v[58:59], v[48:49], v[46:47] op_sel:[1,0,0] op_sel_hi:[1,1,1]
	v_pk_fma_f32 v[46:47], v[60:61], v[76:77], v[46:47] op_sel_hi:[0,1,1]
	v_pk_fma_f32 v[46:47], v[60:61], v[78:79], v[46:47] op_sel:[1,0,0] op_sel_hi:[1,1,1]
	ds_write2st64_b32 v72, v21, v47 offset0:16 offset1:18
	v_pk_fma_f32 v[68:69], v[58:59], v[50:51], v[68:69]
	v_add_f32_dpp v46, v46, v46 quad_perm:[1,0,3,2] row_mask:0xf bank_mask:0xf bound_ctrl:1
	ds_read_b128 v[20:23], v74 offset:39936
	ds_read_b128 v[36:39], v74 offset:40192
	v_add_f32_dpp v46, v46, v46 quad_perm:[2,3,0,1] row_mask:0xf bank_mask:0xf bound_ctrl:1
	ds_read_b128 v[24:27], v74 offset:40448
	ds_read_b128 v[32:35], v75 offset:39936
	v_add_f32_dpp v46, v46, v46 row_half_mirror row_mask:0xf bank_mask:0xf bound_ctrl:1
	ds_read_b128 v[28:31], v74 offset:40704
	v_pk_fma_f32 v[70:71], v[60:61], v[52:53], v[70:71]
	v_add_f32_dpp v46, v46, v46 row_mirror row_mask:0xf bank_mask:0xf bound_ctrl:1
	v_pk_fma_f32 v[58:59], v[54:55], v[46:47], v[68:69] op_sel_hi:[1,0,1]
	v_pk_fma_f32 v[60:61], v[56:57], v[46:47], v[70:71] op_sel_hi:[1,0,1]
	v_pk_mul_f32 v[80:81], v[58:59], v[80:81] op_sel_hi:[0,1]
	v_pk_fma_f32 v[80:81], v[58:59], v[82:83], v[80:81] op_sel:[1,0,0] op_sel_hi:[1,1,1]
	v_pk_fma_f32 v[80:81], v[60:61], v[96:97], v[80:81] op_sel_hi:[0,1,1]
	v_pk_fma_f32 v[80:81], v[60:61], v[98:99], v[80:81] op_sel:[1,0,0] op_sel_hi:[1,1,1]
	v_pk_fma_f32 v[92:93], v[58:59], v[84:85], v[92:93]
	v_pk_fma_f32 v[94:95], v[60:61], v[86:87], v[94:95]
	v_add_f32_dpp v80, v80, v80 quad_perm:[1,0,3,2] row_mask:0xf bank_mask:0xf bound_ctrl:1
	ds_read_b128 v[46:49], v74 offset:43008
	ds_read_b128 v[76:79], v74 offset:43264
	v_add_f32_dpp v80, v80, v80 quad_perm:[2,3,0,1] row_mask:0xf bank_mask:0xf bound_ctrl:1
	ds_read_b128 v[50:53], v74 offset:43520
	ds_read_b128 v[68:71], v75 offset:43008
	v_add_f32_dpp v80, v80, v80 row_half_mirror row_mask:0xf bank_mask:0xf bound_ctrl:1
	ds_read_b128 v[54:57], v74 offset:43776
	s_waitcnt lgkmcnt(5)
; #define LAS __attribute__((address_space(3)))
; #define RW_LDS_WAIT(X) asm volatile("s_waitcnt lgkmcnt(0)" : "+v"(nk##X), "+v"(dd##X), "+v"(bb##X), "+v"(kp##X), "+v"(rr##X), "+v"(vv##X) :: "memory")
; DI void rwkv_scan_phase(int wv, const Params& P, LAS unsigned char* lds) {
;     ...
;                 f32x2 yacc = (f32x2){0.f, 0.f};
;                 unsigned sbt = sba, vbt = vba; LAS float* ybt = yb;
;                 RW_LDS_LOAD(A, 0); RW_LDS_WAIT(A);
; #pragma unroll 1
;                 for (int tt = 0; tt < RW_T; tt += 16) { sbt = sba + (unsigned)tt * 1280u; vbt = vba + (unsigned)tt * 32u; ybt = yb + tt * 128;
;                     RW_LDS_LOAD(B, 1); RW_STEP(A, 0); RW_LDS_WAIT(B);
;                     RW_LDS_LOAD(A, 2); RW_STEP(B, 1); RW_LDS_WAIT(A);
;                     RW_LDS_LOAD(B, 3); RW_STEP(A, 2); RW_LDS_WAIT(B);
;                     RW_LDS_LOAD(A, 4); RW_STEP(B, 3); RW_LDS_WAIT(A);
;                     RW_LDS_LOAD(B, 5); RW_STEP(A, 4); RW_LDS_WAIT(B);
;                     RW_LDS_LOAD(A, 6); RW_STEP(B, 5); RW_LDS_WAIT(A);
;                     RW_LDS_LOAD(B, 7); RW_STEP(A, 6); RW_LDS_WAIT(B);
;                     RW_LDS_LOAD(A, 8); RW_STEP(B, 7); RW_LDS_WAIT(A);
;                     RW_LDS_LOAD(B, 9); RW_STEP(A, 8); RW_LDS_WAIT(B);
;                     RW_LDS_LOAD(A, 10); RW_STEP(B, 9); RW_LDS_WAIT(A);
;                     RW_LDS_LOAD(B, 11); RW_STEP(A, 10); RW_LDS_WAIT(B);
;                     RW_LDS_LOAD(A, 12); RW_STEP(B, 11); RW_LDS_WAIT(A);
;                     RW_LDS_LOAD(B, 13); RW_STEP(A, 12); RW_LDS_WAIT(B);
;                     RW_LDS_LOAD(A, 14); RW_STEP(B, 13); RW_LDS_WAIT(A);
;                     RW_LDS_LOAD(B, 15); RW_STEP(A, 14); RW_LDS_WAIT(B);
;                     RW_LDS_LOAD(A, 16); RW_STEP(B, 15); RW_LDS_WAIT(A);
;                 }
;                 yb[(RW_T - 1) * 128] = yacc[0] + yacc[1];
	v_add_f32_dpp v80, v80, v80 row_mirror row_mask:0xf bank_mask:0xf bound_ctrl:1
	v_pk_fma_f32 v[58:59], v[88:89], v[80:81], v[92:93] op_sel_hi:[1,0,1]
	v_pk_fma_f32 v[60:61], v[90:91], v[80:81], v[94:95] op_sel_hi:[1,0,1]
	v_pk_mul_f32 v[0:1], v[58:59], v[0:1] op_sel_hi:[0,1]
	v_pk_fma_f32 v[0:1], v[58:59], v[2:3], v[0:1] op_sel:[1,0,0] op_sel_hi:[1,1,1]
	v_pk_fma_f32 v[0:1], v[60:61], v[16:17], v[0:1] op_sel_hi:[0,1,1]
	v_pk_fma_f32 v[0:1], v[60:61], v[18:19], v[0:1] op_sel:[1,0,0] op_sel_hi:[1,1,1]
	ds_write2st64_b32 v72, v81, v1 offset0:20 offset1:22
	v_pk_fma_f32 v[12:13], v[58:59], v[4:5], v[12:13]
	v_add_f32_dpp v0, v0, v0 quad_perm:[1,0,3,2] row_mask:0xf bank_mask:0xf bound_ctrl:1
	ds_read_b128 v[80:83], v74 offset:46080
	ds_read_b128 v[96:99], v74 offset:46336
	v_add_f32_dpp v0, v0, v0 quad_perm:[2,3,0,1] row_mask:0xf bank_mask:0xf bound_ctrl:1
	ds_read_b128 v[84:87], v74 offset:46592
	ds_read_b128 v[92:95], v75 offset:46080
	v_add_f32_dpp v0, v0, v0 row_half_mirror row_mask:0xf bank_mask:0xf bound_ctrl:1
	ds_read_b128 v[88:91], v74 offset:46848
	v_pk_fma_f32 v[14:15], v[60:61], v[6:7], v[14:15]
	v_add_f32_dpp v0, v0, v0 row_mirror row_mask:0xf bank_mask:0xf bound_ctrl:1
	v_pk_fma_f32 v[58:59], v[8:9], v[0:1], v[12:13] op_sel_hi:[1,0,1]
	v_pk_fma_f32 v[60:61], v[10:11], v[0:1], v[14:15] op_sel_hi:[1,0,1]
	v_pk_mul_f32 v[20:21], v[58:59], v[20:21] op_sel_hi:[0,1]
	v_pk_fma_f32 v[20:21], v[58:59], v[22:23], v[20:21] op_sel:[1,0,0] op_sel_hi:[1,1,1]
	v_pk_fma_f32 v[20:21], v[60:61], v[36:37], v[20:21] op_sel_hi:[0,1,1]
	v_pk_fma_f32 v[20:21], v[60:61], v[38:39], v[20:21] op_sel:[1,0,0] op_sel_hi:[1,1,1]
	v_pk_fma_f32 v[32:33], v[58:59], v[24:25], v[32:33]
	v_pk_fma_f32 v[34:35], v[60:61], v[26:27], v[34:35]
	v_add_f32_dpp v20, v20, v20 quad_perm:[1,0,3,2] row_mask:0xf bank_mask:0xf bound_ctrl:1
	s_add_i32 s47, s47, 1
	s_add_i32 s42, s42, 0x2000
	v_add_f32_dpp v20, v20, v20 quad_perm:[2,3,0,1] row_mask:0xf bank_mask:0xf bound_ctrl:1
	s_cmp_eq_u32 s42, 0x6000
	s_cselect_b32 s42, 0, s42
	v_add_f32_dpp v20, v20, v20 row_half_mirror row_mask:0xf bank_mask:0xf bound_ctrl:1
	v_add_u32_e32 v67, s42, v62
	s_nop 0
	v_add_f32_dpp v20, v20, v20 row_mirror row_mask:0xf bank_mask:0xf bound_ctrl:1
	v_pk_fma_f32 v[58:59], v[28:29], v[20:21], v[32:33] op_sel_hi:[1,0,1]
	v_pk_fma_f32 v[60:61], v[30:31], v[20:21], v[34:35] op_sel_hi:[1,0,1]
	s_waitcnt lgkmcnt(0)
	s_barrier
	v_xor_b32_e32 v74, 0xc000, v74
	v_xor_b32_e32 v75, 0xc000, v75
	v_pk_mul_f32 v[46:47], v[58:59], v[46:47] op_sel_hi:[0,1]
	v_pk_fma_f32 v[46:47], v[58:59], v[48:49], v[46:47] op_sel:[1,0,0] op_sel_hi:[1,1,1]
	v_pk_fma_f32 v[46:47], v[60:61], v[76:77], v[46:47] op_sel_hi:[0,1,1]
	v_pk_fma_f32 v[46:47], v[60:61], v[78:79], v[46:47] op_sel:[1,0,0] op_sel_hi:[1,1,1]
	ds_write2st64_b32 v72, v21, v47 offset0:24 offset1:26
	v_pk_fma_f32 v[68:69], v[58:59], v[50:51], v[68:69]
	v_add_f32_dpp v46, v46, v46 quad_perm:[1,0,3,2] row_mask:0xf bank_mask:0xf bound_ctrl:1
	ds_read_b128 v[0:3], v74
	ds_read_b128 v[16:19], v74 offset:256
	v_add_f32_dpp v46, v46, v46 quad_perm:[2,3,0,1] row_mask:0xf bank_mask:0xf bound_ctrl:1
	ds_read_b128 v[4:7], v74 offset:512
	ds_read_b128 v[12:15], v75
	v_add_f32_dpp v46, v46, v46 row_half_mirror row_mask:0xf bank_mask:0xf bound_ctrl:1
	ds_read_b128 v[8:11], v74 offset:768
	v_pk_fma_f32 v[70:71], v[60:61], v[52:53], v[70:71]
	v_add_f32_dpp v46, v46, v46 row_mirror row_mask:0xf bank_mask:0xf bound_ctrl:1
	ds_read_b128 v[20:23], v74 offset:3072
	ds_read_b128 v[36:39], v74 offset:3328
	ds_read_b128 v[24:27], v74 offset:3584
	ds_read_b128 v[32:35], v75 offset:3072
	ds_read_b128 v[28:31], v74 offset:3840
	v_pk_fma_f32 v[58:59], v[54:55], v[46:47], v[68:69] op_sel_hi:[1,0,1]
	v_pk_fma_f32 v[60:61], v[56:57], v[46:47], v[70:71] op_sel_hi:[1,0,1]
	v_pk_mul_f32 v[80:81], v[58:59], v[80:81] op_sel_hi:[0,1]
	v_pk_fma_f32 v[80:81], v[58:59], v[82:83], v[80:81] op_sel:[1,0,0] op_sel_hi:[1,1,1]
	v_pk_fma_f32 v[80:81], v[60:61], v[96:97], v[80:81] op_sel_hi:[0,1,1]
	v_pk_fma_f32 v[80:81], v[60:61], v[98:99], v[80:81] op_sel:[1,0,0] op_sel_hi:[1,1,1]
	v_pk_fma_f32 v[92:93], v[58:59], v[84:85], v[92:93]
	v_pk_fma_f32 v[94:95], v[60:61], v[86:87], v[94:95]
	v_add_f32_dpp v80, v80, v80 quad_perm:[1,0,3,2] row_mask:0xf bank_mask:0xf bound_ctrl:1
	ds_read_b128 v[46:49], v74 offset:6144
	ds_read_b128 v[76:79], v74 offset:6400
	v_add_f32_dpp v80, v80, v80 quad_perm:[2,3,0,1] row_mask:0xf bank_mask:0xf bound_ctrl:1
	ds_read_b128 v[50:53], v74 offset:6656
	ds_read_b128 v[68:71], v75 offset:6144
	v_add_f32_dpp v80, v80, v80 row_half_mirror row_mask:0xf bank_mask:0xf bound_ctrl:1
	ds_read_b128 v[54:57], v74 offset:6912
	s_cmpk_eq_i32 s47, 0x200
	v_add_f32_dpp v80, v80, v80 row_mirror row_mask:0xf bank_mask:0xf bound_ctrl:1
	v_pk_fma_f32 v[58:59], v[88:89], v[80:81], v[92:93] op_sel_hi:[1,0,1]
	v_pk_fma_f32 v[60:61], v[90:91], v[80:81], v[94:95] op_sel_hi:[1,0,1]
	s_cbranch_scc0 .Lscan_chunk
	v_add_u32_e32 v40, 0x1e100, v45
	ds_read_b128 v[84:87], v40
	s_waitcnt lgkmcnt(0)
	v_pk_mul_f32 v[64:65], v[84:85], v[58:59]
	v_pk_fma_f32 v[64:65], v[86:87], v[60:61], v[64:65]
	s_nop 0
	v_add_f32_e32 v64, v64, v65
	ds_write2st64_b32 v72, v81, v64 offset0:28 offset1:30
	s_waitcnt lgkmcnt(0)
	s_barrier
